# UP idle tail (WGs>=172): window-output copy + hand-written W_down transposes, both removed from prep
# speedup vs baseline: 1.0154x; 1.0047x over previous
; __device__ __forceinline__ void prep_phase(const Params& p, char* lds) {
;     ...
;     float* scr = (float*)(lds + wid * 8704);
;     constexpr int I_IN = 32 * 104, I_GLU = 16 * 64, I_ATT = 16 * 32, I_O = 32 * 32, I_UP = 32 * 176, I_DN = 88 * 32;
;     constexpr int NIT = I_IN + I_GLU + I_ATT + I_O + I_UP + I_DN;
;     for (int it = gw; it < NIT; it += NGW) {
;       int r = it;
;       if (r < I_IN) { transpose_item<0>(p.in[7], 1024, DIN, (bf16_t*)(ws + OFF_WIN), 0, scr, r, lane); continue; } r -= I_IN;
;       if (r < I_GLU) { transpose_item<1>(p.in[16], 512, 2048, (bf16_t*)(ws + OFF_WGLU), 1024, scr, r, lane); continue; } r -= I_GLU;
;       if (r < I_ATT) { transpose_item<0>(p.in[18], 512, 1024, (bf16_t*)(ws + OFF_WATT), 0, scr, r, lane); continue; } r -= I_ATT;
;       if (r < I_O) { transpose_item<0>(p.in[19], 1024, 1024, (bf16_t*)(ws + OFF_WO), 0, scr, r, lane); continue; } r -= I_O;
;       if (r < I_UP) { transpose_item<1>(p.in[22], 1024, 5632, (bf16_t*)(ws + OFF_WUP), DFF, scr, r, lane); continue; } r -= I_UP;
;       transpose_item<0>(p.in[25], DFF, 1024, (bf16_t*)(ws + OFF_WDN), 0, scr, r, lane);
;     }
.LBB0_17:
	s_or_b64 exec, exec, s[0:1]
	v_lshrrev_b32_e32 v183, 6, v0
	v_readlane_b32 s0, v244, 33
	v_and_b32_e32 v184, 63, v0
	v_and_b32_e32 v135, 31, v0
	v_lshl_or_b32 v182, s0, 3, v183
	s_lshl_b32 s0, s33, 3
	v_writelane_b32 v244, s0, 51
	v_lshlrev_b32_e32 v43, 3, v0
	v_lshrrev_b32_e32 v134, 3, v0
	v_writelane_b32 v244, s1, 52
	s_movk_i32 s0, 0x3800
	v_cmp_gt_i32_e32 vcc, s0, v182
	s_and_saveexec_b64 s[0:1], vcc
	s_cbranch_execz .LBB0_40
	s_movk_i32 s3, 0x2200
	v_lshrrev_b32_e32 v45, 2, v184
	v_and_b32_e32 v3, 24, v43
	v_and_b32_e32 v4, 16, v0
	v_readlane_b32 s4, v244, 0
	v_mad_u32_u24 v1, v183, s3, 0
	v_lshlrev_b32_e32 v28, 2, v135
	v_mul_u32_u24_e32 v8, 0x84, v3
	v_and_or_b32 v9, v45, 3, v4
	v_lshlrev_b32_e32 v4, 1, v3
	v_mov_b32_e32 v5, 0
	v_readlane_b32 s5, v244, 1
	v_readlane_b32 s6, v244, 2
	v_readlane_b32 s7, v244, 3
	v_and_b32_e32 v3, 60, v184
	v_or_b32_e32 v49, 16, v45
	v_add_u32_e32 v44, v1, v28
	v_lshl_add_u64 v[16:17], s[6:7], 0, v[4:5]
	s_mov_b64 s[4:5], 0xdc80000
	v_add3_u32 v46, v1, v8, v3
	v_lshrrev_b32_e32 v1, 1, v49
	v_lshl_add_u64 v[6:7], v[16:17], 0, s[4:5]
	v_and_b32_e32 v47, 4, v134
	v_and_b32_e32 v50, 12, v1
	s_mov_b64 s[4:5], 0xd180000
	v_or_b32_e32 v48, v9, v47
	v_or_b32_e32 v51, v50, v9
	v_lshl_add_u64 v[8:9], v[16:17], 0, s[4:5]
	s_mov_b64 s[4:5], 0xcf80000
	v_lshl_add_u64 v[10:11], v[16:17], 0, s[4:5]
	s_mov_b64 s[4:5], 0xce80000
	v_lshl_add_u64 v[12:13], v[16:17], 0, s[4:5]
	s_mov_b64 s[4:5], 0xcc80000
	v_lshl_add_u64 v[14:15], v[16:17], 0, s[4:5]
	s_mov_b64 s[4:5], 0xc600000
	v_lshl_add_u64 v[16:17], v[16:17], 0, s[4:5]
	v_readlane_b32 s4, v244, 4
	v_mov_b32_e32 v29, v5
	v_readlane_b32 s5, v244, 5
	v_readlane_b32 s6, v244, 6
	v_readlane_b32 s7, v244, 7
	v_readlane_b32 s8, v244, 8
	v_readlane_b32 s9, v244, 9
	v_readlane_b32 s10, v244, 10
	v_readlane_b32 s11, v244, 11
	v_lshl_add_u64 v[18:19], s[6:7], 0, v[28:29]
	v_readlane_b32 s4, v244, 35
	v_readlane_b32 s5, v244, 36
	v_readlane_b32 s6, v244, 37
	v_readlane_b32 s7, v244, 38
	v_readlane_b32 s8, v244, 39
	v_readlane_b32 s9, v244, 40
	v_readlane_b32 s10, v244, 41
	v_readlane_b32 s11, v244, 42
	v_readlane_b32 s12, v244, 43
	v_readlane_b32 s13, v244, 44
	v_readlane_b32 s14, v244, 45
	v_readlane_b32 s15, v244, 46
	v_readlane_b32 s16, v244, 47
	v_readlane_b32 s17, v244, 48
	v_readlane_b32 s18, v244, 49
	v_readlane_b32 s19, v244, 50
	v_lshrrev_b32_e32 v2, 5, v184
	v_lshl_add_u64 v[20:21], s[16:17], 0, v[28:29]
	v_lshl_add_u64 v[22:23], s[10:11], 0, v[28:29]
	v_lshl_add_u64 v[24:25], s[8:9], 0, v[28:29]
	v_lshl_add_u64 v[26:27], s[4:5], 0, v[28:29]
	v_readlane_b32 s4, v244, 14
	v_readlane_b32 s5, v244, 15
	v_readlane_b32 s16, v244, 26
	v_readlane_b32 s17, v244, 27
	v_readlane_b32 s18, v244, 28
	v_readlane_b32 s19, v244, 29
	v_or_b32_e32 v1, 2, v2
	v_or_b32_e32 v3, 6, v2
	v_or_b32_e32 v30, 4, v2
	v_or_b32_e32 v31, 10, v2
	v_or_b32_e32 v32, 8, v2
	v_or_b32_e32 v34, 12, v2
	v_or_b32_e32 v33, 14, v2
	v_or_b32_e32 v36, 16, v2
	v_or_b32_e32 v35, 18, v2
	v_or_b32_e32 v38, 20, v2
	v_or_b32_e32 v37, 22, v2
	v_or_b32_e32 v40, 24, v2
	v_or_b32_e32 v39, 26, v2
	v_or_b32_e32 v42, 28, v2
	v_or_b32_e32 v41, 30, v2
	v_lshl_add_u64 v[28:29], s[18:19], 0, v[28:29]
	v_mul_u32_u24_e32 v52, 0x84, v2
	v_mul_u32_u24_e32 v53, 0x84, v1
	v_mul_u32_u24_e32 v54, 0x84, v30
	v_mul_u32_u24_e32 v55, 0x84, v3
	s_mov_b64 s[4:5], 0
	s_movk_i32 s3, 0xcff
	s_movk_i32 s16, 0x10ff
	s_movk_i32 s17, 0x12ff
	s_movk_i32 s18, 0x16ff
	s_movk_i32 s19, 0x2cff
	s_movk_i32 s20, 0xb00
	s_movk_i32 s21, 0x63
	s_movk_i32 s22, 0x400
	s_mov_b32 s23, 0x4ec4ec4f
	s_movk_i32 s24, 0xff98
	s_movk_i32 s25, 0x3400
	s_movk_i32 s26, 0x2cff
	v_mul_u32_u24_e32 v56, 0x84, v32
	v_mul_u32_u24_e32 v57, 0x84, v31
	v_mul_u32_u24_e32 v58, 0x84, v34
	v_mul_u32_u24_e32 v59, 0x84, v33
	v_mul_u32_u24_e32 v60, 0x84, v36
	v_mul_u32_u24_e32 v61, 0x84, v35
	v_mul_u32_u24_e32 v62, 0x84, v38
	v_mul_u32_u24_e32 v63, 0x84, v37
	v_mul_u32_u24_e32 v64, 0x84, v40
	v_mul_u32_u24_e32 v65, 0x84, v39
	v_mul_u32_u24_e32 v66, 0x84, v42
	v_mul_u32_u24_e32 v67, 0x84, v41
	v_mov_b32_e32 v68, 0xfffff500
	v_mov_b32_e32 v69, 0xfffffc00
	v_mov_b32_e32 v70, v182
	v_readlane_b32 s6, v244, 16
	v_readlane_b32 s7, v244, 17
	v_readlane_b32 s8, v244, 18
	v_readlane_b32 s9, v244, 19
	v_readlane_b32 s10, v244, 20
	v_readlane_b32 s11, v244, 21
	v_readlane_b32 s12, v244, 22
	v_readlane_b32 s13, v244, 23
	v_readlane_b32 s14, v244, 24
	v_readlane_b32 s15, v244, 25
	s_branch .LBB0_20

; __device__ __forceinline__ void prep_phase(const Params& p, char* lds) {
;     ...
;     for (int i = gt; i < 128 * 124 * 32; i += NGT) {
;       const int c4 = i & 31, w = (i >> 5) % 124, b = i / (124 * 32);
;       const size_t so = ((size_t)b * 128 + w + 4) * 128 + c4 * 4, dof = ((size_t)b * 128 + w) * 128 + c4 * 4;
;       *(f32x4*)(p.out + O_KS + dof) = *(const f32x4*)(ck + so);
;       *(f32x4*)(p.out + O_VS + dof) = *(const f32x4*)(cv + so);
;     }
.LBB0_1103:
	s_waitcnt vmcnt(0)
	s_barrier
	v_readlane_b32 s98, v244, 33
	s_nop 3
	s_cmp_eq_u32 s33, 0x100
	s_cselect_b32 s99, 172, 0
	s_cmp_lt_u32 s98, s99
	s_cbranch_scc1 .Lwin_skip
	v_writelane_b32 v246, s0, 0
	v_writelane_b32 v246, s1, 1
	v_writelane_b32 v246, s2, 2
	v_writelane_b32 v246, s3, 3
	v_writelane_b32 v246, s4, 4
	v_writelane_b32 v246, s5, 5
	v_writelane_b32 v246, s6, 6
	v_writelane_b32 v246, s7, 7
	v_writelane_b32 v246, s8, 8
	v_writelane_b32 v246, s9, 9
	v_writelane_b32 v246, s10, 10
	v_writelane_b32 v246, s11, 11
	v_writelane_b32 v246, s12, 12
	v_writelane_b32 v246, s13, 13
	v_writelane_b32 v246, s14, 14
	v_writelane_b32 v246, s15, 15
	v_writelane_b32 v246, s16, 16
	v_writelane_b32 v246, s17, 17
	v_writelane_b32 v246, s18, 18
	v_writelane_b32 v246, s19, 19
	v_writelane_b32 v246, s20, 20
	v_writelane_b32 v246, s21, 21
	v_writelane_b32 v246, s22, 22
	v_writelane_b32 v246, s23, 23
	v_writelane_b32 v246, s24, 24
	v_writelane_b32 v246, s25, 25
	s_sub_u32 s98, s98, s99
	v_lshl_or_b32 v245, s98, 9, v0
	s_sub_u32 s100, s33, s99
	s_lshl_b32 s101, s100, 9
	v_readlane_b32 s12, v244, 18
	v_readlane_b32 s13, v244, 19
	v_readlane_b32 s14, v244, 20
	v_readlane_b32 s15, v244, 21
	v_readlane_b32 s8, v244, 0
	v_readlane_b32 s9, v244, 1
	s_nop 1
	s_add_u32 s4, s8, 0x4300000
	s_addc_u32 s5, s9, 0
	s_add_u32 s6, s8, 0x4b00000
	s_addc_u32 s7, s9, 0
	v_mov_b32_e32 v104, v245
	v_mov_b32_e32 v100, 0x2108422
.Lwin_l5:
	v_mov_b32_e32 v105, s101
	v_mad_u32_u24 v105, v105, 0, v104
	v_and_b32_e32 v103, 31, v105
	v_lshrrev_b32_e32 v102, 5, v105
	v_mul_hi_u32 v101, v102, v100
	v_mul_u32_u24_e32 v107, 0x7c, v101
	v_sub_u32_e32 v102, v102, v107
	v_lshlrev_b32_e32 v103, 4, v103
	v_lshl_add_u32 v103, v102, 9, v103
	v_lshl_add_u32 v107, v101, 16, v103
	v_add_u32_e32 v106, 0x800, v107
	v_mov_b32_e32 v109, s101
	v_mad_u32_u24 v109, v109, 1, v104
	v_and_b32_e32 v103, 31, v109
	v_lshrrev_b32_e32 v102, 5, v109
	v_mul_hi_u32 v101, v102, v100
	v_mul_u32_u24_e32 v111, 0x7c, v101
	v_sub_u32_e32 v102, v102, v111
	v_lshlrev_b32_e32 v103, 4, v103
	v_lshl_add_u32 v103, v102, 9, v103
	v_lshl_add_u32 v111, v101, 16, v103
	v_add_u32_e32 v110, 0x800, v111
	v_mov_b32_e32 v113, s101
	v_mad_u32_u24 v113, v113, 2, v104
	v_and_b32_e32 v103, 31, v113
	v_lshrrev_b32_e32 v102, 5, v113
	v_mul_hi_u32 v101, v102, v100
	v_mul_u32_u24_e32 v115, 0x7c, v101
	v_sub_u32_e32 v102, v102, v115
	v_lshlrev_b32_e32 v103, 4, v103
	v_lshl_add_u32 v103, v102, 9, v103
	v_lshl_add_u32 v115, v101, 16, v103
	v_add_u32_e32 v114, 0x800, v115
	v_mov_b32_e32 v117, s101
	v_mad_u32_u24 v117, v117, 3, v104
	v_and_b32_e32 v103, 31, v117
	v_lshrrev_b32_e32 v102, 5, v117
	v_mul_hi_u32 v101, v102, v100
	v_mul_u32_u24_e32 v119, 0x7c, v101
	v_sub_u32_e32 v102, v102, v119
	v_lshlrev_b32_e32 v103, 4, v103
	v_lshl_add_u32 v103, v102, 9, v103
	v_lshl_add_u32 v119, v101, 16, v103
	v_add_u32_e32 v118, 0x800, v119
	v_mov_b32_e32 v121, s101
	v_mad_u32_u24 v121, v121, 4, v104
	v_and_b32_e32 v103, 31, v121
	v_lshrrev_b32_e32 v102, 5, v121
	v_mul_hi_u32 v101, v102, v100
	v_mul_u32_u24_e32 v123, 0x7c, v101
	v_sub_u32_e32 v102, v102, v123
	v_lshlrev_b32_e32 v103, 4, v103
	v_lshl_add_u32 v103, v102, 9, v103
	v_lshl_add_u32 v123, v101, 16, v103
	v_add_u32_e32 v122, 0x800, v123
	v_mov_b32_e32 v125, s101
	v_mad_u32_u24 v125, v125, 5, v104
	v_and_b32_e32 v103, 31, v125
	v_lshrrev_b32_e32 v102, 5, v125
	v_mul_hi_u32 v101, v102, v100
	v_mul_u32_u24_e32 v127, 0x7c, v101
	v_sub_u32_e32 v102, v102, v127
	v_lshlrev_b32_e32 v103, 4, v103
	v_lshl_add_u32 v103, v102, 9, v103
	v_lshl_add_u32 v127, v101, 16, v103
	v_add_u32_e32 v126, 0x800, v127
	v_cmp_gt_u32_e32 vcc, 0x7c000, v105
	s_and_saveexec_b64 s[10:11], vcc
	global_load_dwordx4 v[132:135], v106, s[12:13]
	global_load_dwordx4 v[136:139], v106, s[14:15]
	s_or_b64 exec, exec, s[10:11]
	v_cmp_gt_u32_e32 vcc, 0x7c000, v109
	s_and_saveexec_b64 s[10:11], vcc
	global_load_dwordx4 v[140:143], v110, s[12:13]
	global_load_dwordx4 v[144:147], v110, s[14:15]
	s_or_b64 exec, exec, s[10:11]
	v_cmp_gt_u32_e32 vcc, 0x7c000, v113
	s_and_saveexec_b64 s[10:11], vcc
	global_load_dwordx4 v[148:151], v114, s[12:13]
	global_load_dwordx4 v[152:155], v114, s[14:15]
	s_or_b64 exec, exec, s[10:11]
	v_cmp_gt_u32_e32 vcc, 0x7c000, v117
	s_and_saveexec_b64 s[10:11], vcc
	global_load_dwordx4 v[156:159], v118, s[12:13]
	global_load_dwordx4 v[160:163], v118, s[14:15]
	s_or_b64 exec, exec, s[10:11]
	v_cmp_gt_u32_e32 vcc, 0x7c000, v121
	s_and_saveexec_b64 s[10:11], vcc
	global_load_dwordx4 v[164:167], v122, s[12:13]
	global_load_dwordx4 v[168:171], v122, s[14:15]
	s_or_b64 exec, exec, s[10:11]
	v_cmp_gt_u32_e32 vcc, 0x7c000, v125
	s_and_saveexec_b64 s[10:11], vcc
	global_load_dwordx4 v[172:175], v126, s[12:13]
	global_load_dwordx4 v[176:179], v126, s[14:15]
	s_or_b64 exec, exec, s[10:11]
	s_waitcnt vmcnt(0)
	v_cmp_gt_u32_e32 vcc, 0x7c000, v105
	s_and_saveexec_b64 s[10:11], vcc
	global_store_dwordx4 v107, v[132:135], s[4:5] sc1
	global_store_dwordx4 v107, v[136:139], s[6:7] sc1
	s_or_b64 exec, exec, s[10:11]
	v_cmp_gt_u32_e32 vcc, 0x7c000, v109
	s_and_saveexec_b64 s[10:11], vcc
	global_store_dwordx4 v111, v[140:143], s[4:5] sc1
	global_store_dwordx4 v111, v[144:147], s[6:7] sc1
	s_or_b64 exec, exec, s[10:11]
	v_cmp_gt_u32_e32 vcc, 0x7c000, v113
	s_and_saveexec_b64 s[10:11], vcc
	global_store_dwordx4 v115, v[148:151], s[4:5] sc1
	global_store_dwordx4 v115, v[152:155], s[6:7] sc1
	s_or_b64 exec, exec, s[10:11]
	v_cmp_gt_u32_e32 vcc, 0x7c000, v117
	s_and_saveexec_b64 s[10:11], vcc
	global_store_dwordx4 v119, v[156:159], s[4:5] sc1
	global_store_dwordx4 v119, v[160:163], s[6:7] sc1
	s_or_b64 exec, exec, s[10:11]
	v_cmp_gt_u32_e32 vcc, 0x7c000, v121
	s_and_saveexec_b64 s[10:11], vcc
	global_store_dwordx4 v123, v[164:167], s[4:5] sc1
	global_store_dwordx4 v123, v[168:171], s[6:7] sc1
	s_or_b64 exec, exec, s[10:11]
	v_cmp_gt_u32_e32 vcc, 0x7c000, v125
	s_and_saveexec_b64 s[10:11], vcc
	global_store_dwordx4 v127, v[172:175], s[4:5] sc1
	global_store_dwordx4 v127, v[176:179], s[6:7] sc1
	s_or_b64 exec, exec, s[10:11]
	v_mov_b32_e32 v103, s101
	v_mad_u32_u24 v104, v103, 6, v104
	v_cmp_gt_u32_e32 vcc, 0x7c000, v104
	s_cbranch_vccnz .Lwin_l5
; template <int MODE>
; __device__ __forceinline__ void transpose_item(const float* __restrict__ W, int K, int N, bf16_t* __restrict__ WT, int HH, float* scr, int item, int lane) {
;   const int nblk = N / 32, kb = item / nblk, nb = item - kb * nblk, k0 = 32 * kb, n0 = 32 * nb;
; #pragma unroll 8
;   for (int i = 0; i < 16; ++i) { const int kk = 2 * i + (lane >> 5); scr[kk * 33 + (lane & 31)] = W[(size_t)(k0 + kk) * N + n0 + (lane & 31)]; }
; __device__ __forceinline__ void prep_phase(const Params& p, char* lds) {
;     ...
;       transpose_item<0>(p.in[25], DFF, 1024, (bf16_t*)(ws + OFF_WDN), 0, scr, r, lane);
	v_readlane_b32 s12, v244, 6
	v_readlane_b32 s13, v244, 7
	v_readlane_b32 s14, v244, 2
	v_readlane_b32 s15, v244, 3
	v_readfirstlane_b32 s16, v0
	s_nop 3
	s_lshr_b32 s16, s16, 6
	s_add_u32 s14, s14, 0xdc80000
	s_addc_u32 s15, s15, 0
	s_lshl_b32 s17, s98, 3
	s_add_u32 s17, s17, s16
	s_lshl_b32 s18, s100, 3
	s_mul_i32 s16, s16, 0x2200
	v_and_b32_e32 v100, 63, v0
	v_lshrrev_b32_e32 v101, 5, v100
	v_and_b32_e32 v102, 31, v100
	v_mul_u32_u24_e32 v103, 33, v101
	v_add_u32_e32 v103, v103, v102
	v_lshl_add_u32 v103, v103, 2, s16
	v_and_b32_e32 v108, 3, v100
	v_lshrrev_b32_e32 v109, 2, v100
	v_mul_u32_u24_e32 v104, 0x108, v108
	v_add_u32_e32 v104, v104, v109
	v_lshl_add_u32 v104, v104, 2, s16
	v_lshl_add_u32 v106, v101, 10, v102
	v_lshlrev_b32_e32 v106, 2, v106
	v_bfe_u32 v105, v100, 4, 1
	v_lshlrev_b32_e32 v105, 4, v105
	v_lshl_add_u32 v105, v101, 2, v105
	v_and_b32_e32 v107, 3, v109
	v_add_u32_e32 v105, v105, v107
	v_mul_u32_u24_e32 v105, 0x1600, v105
	v_lshl_add_u32 v105, v108, 4, v105
	v_add_u32_e32 v107, 0xb000, v105
	s_cmpk_lt_u32 s17, 0xb00
	s_cbranch_scc0 .Ldn_done
.Ldn_loop:
	s_lshr_b32 s24, s17, 5
	s_and_b32 s25, s17, 31
	s_lshl_b32 s22, s24, 17
	s_lshl_b32 s23, s25, 7
	s_add_u32 s22, s22, s23
	s_add_u32 s0, s12, s22
	s_addc_u32 s1, s13, 0
	s_mul_i32 s22, s25, 0x2c000
	s_lshl_b32 s23, s24, 6
	s_add_u32 s22, s22, s23
	s_add_u32 s2, s14, s22
	s_addc_u32 s3, s15, 0
	s_add_u32 s19, s17, s18
	s_cmpk_lt_u32 s19, 0xb00
	s_cselect_b32 s20, 1, 0
	s_lshr_b32 s24, s19, 5
	s_and_b32 s25, s19, 31
	s_lshl_b32 s22, s24, 17
	s_lshl_b32 s23, s25, 7
	s_add_u32 s22, s22, s23
	s_add_u32 s4, s12, s22
	s_addc_u32 s5, s13, 0
	s_mul_i32 s22, s25, 0x2c000
	s_lshl_b32 s23, s24, 6
	s_add_u32 s22, s22, s23
	s_add_u32 s6, s14, s22
	s_addc_u32 s7, s15, 0
	global_load_dword v110, v106, s[0:1]
	s_add_u32 s0, s0, 0x2000
	s_addc_u32 s1, s1, 0
	global_load_dword v111, v106, s[0:1]
	s_add_u32 s0, s0, 0x2000
	s_addc_u32 s1, s1, 0
	global_load_dword v112, v106, s[0:1]
	s_add_u32 s0, s0, 0x2000
	s_addc_u32 s1, s1, 0
	global_load_dword v113, v106, s[0:1]
	s_add_u32 s0, s0, 0x2000
	s_addc_u32 s1, s1, 0
	global_load_dword v114, v106, s[0:1]
	s_add_u32 s0, s0, 0x2000
	s_addc_u32 s1, s1, 0
	global_load_dword v115, v106, s[0:1]
	s_add_u32 s0, s0, 0x2000
	s_addc_u32 s1, s1, 0
	global_load_dword v116, v106, s[0:1]
	s_add_u32 s0, s0, 0x2000
	s_addc_u32 s1, s1, 0
	global_load_dword v117, v106, s[0:1]
	s_add_u32 s0, s0, 0x2000
	s_addc_u32 s1, s1, 0
	global_load_dword v118, v106, s[0:1]
	s_add_u32 s0, s0, 0x2000
	s_addc_u32 s1, s1, 0
	global_load_dword v119, v106, s[0:1]
	s_add_u32 s0, s0, 0x2000
	s_addc_u32 s1, s1, 0
	global_load_dword v120, v106, s[0:1]
	s_add_u32 s0, s0, 0x2000
	s_addc_u32 s1, s1, 0
	global_load_dword v121, v106, s[0:1]
	s_add_u32 s0, s0, 0x2000
	s_addc_u32 s1, s1, 0
	global_load_dword v122, v106, s[0:1]
	s_add_u32 s0, s0, 0x2000
	s_addc_u32 s1, s1, 0
	global_load_dword v123, v106, s[0:1]
	s_add_u32 s0, s0, 0x2000
	s_addc_u32 s1, s1, 0
	global_load_dword v124, v106, s[0:1]
	s_add_u32 s0, s0, 0x2000
	s_addc_u32 s1, s1, 0
	global_load_dword v125, v106, s[0:1]
	s_cmp_eq_u32 s20, 0
	s_cbranch_scc1 .Ldn_noB1
	global_load_dword v126, v106, s[4:5]
	s_add_u32 s4, s4, 0x2000
	s_addc_u32 s5, s5, 0
	global_load_dword v127, v106, s[4:5]
	s_add_u32 s4, s4, 0x2000
	s_addc_u32 s5, s5, 0
	global_load_dword v128, v106, s[4:5]
	s_add_u32 s4, s4, 0x2000
	s_addc_u32 s5, s5, 0
	global_load_dword v129, v106, s[4:5]
	s_add_u32 s4, s4, 0x2000
	s_addc_u32 s5, s5, 0
	global_load_dword v130, v106, s[4:5]
	s_add_u32 s4, s4, 0x2000
	s_addc_u32 s5, s5, 0
	global_load_dword v131, v106, s[4:5]
	s_add_u32 s4, s4, 0x2000
	s_addc_u32 s5, s5, 0
	global_load_dword v132, v106, s[4:5]
	s_add_u32 s4, s4, 0x2000
	s_addc_u32 s5, s5, 0
	global_load_dword v133, v106, s[4:5]
	s_add_u32 s4, s4, 0x2000
	s_addc_u32 s5, s5, 0
	global_load_dword v134, v106, s[4:5]
	s_add_u32 s4, s4, 0x2000
	s_addc_u32 s5, s5, 0
	global_load_dword v135, v106, s[4:5]
	s_add_u32 s4, s4, 0x2000
	s_addc_u32 s5, s5, 0
	global_load_dword v136, v106, s[4:5]
	s_add_u32 s4, s4, 0x2000
	s_addc_u32 s5, s5, 0
	global_load_dword v137, v106, s[4:5]
	s_add_u32 s4, s4, 0x2000
	s_addc_u32 s5, s5, 0
	global_load_dword v138, v106, s[4:5]
	s_add_u32 s4, s4, 0x2000
	s_addc_u32 s5, s5, 0
	global_load_dword v139, v106, s[4:5]
	s_add_u32 s4, s4, 0x2000
	s_addc_u32 s5, s5, 0
	global_load_dword v140, v106, s[4:5]
	s_add_u32 s4, s4, 0x2000
	s_addc_u32 s5, s5, 0
	global_load_dword v141, v106, s[4:5]
	s_waitcnt vmcnt(16)
	s_branch .Ldn_wA

; __device__ __forceinline__ unsigned pk2(float lo, float hi) { f32x2 v = {lo, hi}; bf16v2_t b = __builtin_convertvector(v, bf16v2_t); return __builtin_bit_cast(unsigned, b); }
; template <int MODE>
; __device__ __forceinline__ void transpose_item(const float* __restrict__ W, int K, int N, bf16_t* __restrict__ WT, int HH, float* scr, int item, int lane) {
;     ...
;   for (int i = 0; i < 16; ++i) { const int kk = 2 * i + (lane >> 5); scr[kk * 33 + (lane & 31)] = W[(size_t)(k0 + kk) * N + n0 + (lane & 31)]; }
;   asm volatile("s_waitcnt lgkmcnt(0)" ::: "memory");
;   const int c = lane & 3;
; #pragma unroll
;   for (int j = 0; j < 2; ++j) {
;     const int n = (lane >> 2) + 16 * j; const float* sp = scr + (8 * c) * 33 + n;
;     u32x4 o; o.x = pk2(sp[0], sp[33]); o.y = pk2(sp[66], sp[99]); o.z = pk2(sp[132], sp[165]); o.w = pk2(sp[198], sp[231]);
;     *(u32x4*)(WT + (size_t)dest_row<MODE>(n0 + n, HH) * K + k0 + 8 * c) = o;
;   }
;   asm volatile("s_waitcnt lgkmcnt(0)" ::: "memory");
.Ldn_wA:
	ds_write_b32 v103, v110 offset:0
	ds_write_b32 v103, v111 offset:264
	ds_write_b32 v103, v112 offset:528
	ds_write_b32 v103, v113 offset:792
	ds_write_b32 v103, v114 offset:1056
	ds_write_b32 v103, v115 offset:1320
	ds_write_b32 v103, v116 offset:1584
	ds_write_b32 v103, v117 offset:1848
	ds_write_b32 v103, v118 offset:2112
	ds_write_b32 v103, v119 offset:2376
	ds_write_b32 v103, v120 offset:2640
	ds_write_b32 v103, v121 offset:2904
	ds_write_b32 v103, v122 offset:3168
	ds_write_b32 v103, v123 offset:3432
	ds_write_b32 v103, v124 offset:3696
	ds_write_b32 v103, v125 offset:3960
	s_cmp_eq_u32 s20, 0
	s_cbranch_scc1 .Ldn_noB2
	s_waitcnt vmcnt(0)
	ds_write_b32 v103, v126 offset:4224
	ds_write_b32 v103, v127 offset:4488
	ds_write_b32 v103, v128 offset:4752
	ds_write_b32 v103, v129 offset:5016
	ds_write_b32 v103, v130 offset:5280
	ds_write_b32 v103, v131 offset:5544
	ds_write_b32 v103, v132 offset:5808
	ds_write_b32 v103, v133 offset:6072
	ds_write_b32 v103, v134 offset:6336
	ds_write_b32 v103, v135 offset:6600
	ds_write_b32 v103, v136 offset:6864
	ds_write_b32 v103, v137 offset:7128
	ds_write_b32 v103, v138 offset:7392
	ds_write_b32 v103, v139 offset:7656
	ds_write_b32 v103, v140 offset:7920
	ds_write_b32 v103, v141 offset:8184
.Ldn_noB2:
	ds_read_b32 v142, v104 offset:0
	ds_read_b32 v143, v104 offset:132
	ds_read_b32 v144, v104 offset:264
	ds_read_b32 v145, v104 offset:396
	ds_read_b32 v146, v104 offset:528
	ds_read_b32 v147, v104 offset:660
	ds_read_b32 v148, v104 offset:792
	ds_read_b32 v149, v104 offset:924
	ds_read_b32 v150, v104 offset:64
	ds_read_b32 v151, v104 offset:196
	ds_read_b32 v152, v104 offset:328
	ds_read_b32 v153, v104 offset:460
	ds_read_b32 v154, v104 offset:592
	ds_read_b32 v155, v104 offset:724
	ds_read_b32 v156, v104 offset:856
	ds_read_b32 v157, v104 offset:988
	s_cmp_eq_u32 s20, 0
	s_cbranch_scc1 .Ldn_noB3
	ds_read_b32 v158, v104 offset:4224
	ds_read_b32 v159, v104 offset:4356
	ds_read_b32 v160, v104 offset:4488
	ds_read_b32 v161, v104 offset:4620
	ds_read_b32 v162, v104 offset:4752
	ds_read_b32 v163, v104 offset:4884
	ds_read_b32 v164, v104 offset:5016
	ds_read_b32 v165, v104 offset:5148
	ds_read_b32 v166, v104 offset:4288
	ds_read_b32 v167, v104 offset:4420
	ds_read_b32 v168, v104 offset:4552
	ds_read_b32 v169, v104 offset:4684
	ds_read_b32 v170, v104 offset:4816
	ds_read_b32 v171, v104 offset:4948
	ds_read_b32 v172, v104 offset:5080
	ds_read_b32 v173, v104 offset:5212
.Ldn_noB3:
	s_waitcnt lgkmcnt(0)
	v_cvt_pk_bf16_f32 v142, v142, v143
	v_cvt_pk_bf16_f32 v143, v144, v145
	v_cvt_pk_bf16_f32 v144, v146, v147
	v_cvt_pk_bf16_f32 v145, v148, v149
	global_store_dwordx4 v105, v[142:145], s[2:3] sc1
	v_cvt_pk_bf16_f32 v150, v150, v151
	v_cvt_pk_bf16_f32 v151, v152, v153
	v_cvt_pk_bf16_f32 v152, v154, v155
	v_cvt_pk_bf16_f32 v153, v156, v157
	global_store_dwordx4 v107, v[150:153], s[2:3] sc1
	s_cmp_eq_u32 s20, 0
	s_cbranch_scc1 .Ldn_noB4
	v_cvt_pk_bf16_f32 v158, v158, v159
	v_cvt_pk_bf16_f32 v159, v160, v161
	v_cvt_pk_bf16_f32 v160, v162, v163
	v_cvt_pk_bf16_f32 v161, v164, v165
	global_store_dwordx4 v105, v[158:161], s[6:7] sc1
	v_cvt_pk_bf16_f32 v166, v166, v167
	v_cvt_pk_bf16_f32 v167, v168, v169
	v_cvt_pk_bf16_f32 v168, v170, v171
	v_cvt_pk_bf16_f32 v169, v172, v173
	global_store_dwordx4 v107, v[166:169], s[6:7] sc1
.Ldn_noB4:
	s_lshl_b32 s19, s18, 1
	s_add_u32 s17, s17, s19
	s_cmpk_lt_u32 s17, 0xb00
	s_cbranch_scc1 .Ldn_loop
.Ldn_done:
	v_readlane_b32 s0, v246, 0
	v_readlane_b32 s1, v246, 1
	v_readlane_b32 s2, v246, 2
	v_readlane_b32 s3, v246, 3
	v_readlane_b32 s4, v246, 4
	v_readlane_b32 s5, v246, 5
	v_readlane_b32 s6, v246, 6
	v_readlane_b32 s7, v246, 7
	v_readlane_b32 s8, v246, 8
	v_readlane_b32 s9, v246, 9
	v_readlane_b32 s10, v246, 10
	v_readlane_b32 s11, v246, 11
	v_readlane_b32 s12, v246, 12
	v_readlane_b32 s13, v246, 13
	v_readlane_b32 s14, v246, 14
	v_readlane_b32 s15, v246, 15
	v_readlane_b32 s16, v246, 16
	v_readlane_b32 s17, v246, 17
	v_readlane_b32 s18, v246, 18
	v_readlane_b32 s19, v246, 19
	v_readlane_b32 s20, v246, 20
	v_readlane_b32 s21, v246, 21
	v_readlane_b32 s22, v246, 22
	v_readlane_b32 s23, v246, 23
	v_readlane_b32 s24, v246, 24
	v_readlane_b32 s25, v246, 25
	s_waitcnt vmcnt(0) lgkmcnt(0)
	s_barrier
